# P8 k-loop: per-phase vmcnt(10) waits replace the two vmcnt(6) drains (each LDS-DMA load gets 5 phases of latency budget instead of 3)
# speedup vs baseline: 1.0019x; 1.0019x over previous
.Lp8_nostage:
	ds_read_b128 v[130:133], v240
	ds_read_b128 v[134:137], v240 offset:1024
	ds_read_b128 v[138:141], v240 offset:2048
	ds_read_b128 v[142:145], v240 offset:3072
	s_add_u32 s50, s48, 0xfff80080
	s_addc_u32 s51, s49, -1
	s_cmp_eq_u32 s80, s87
	s_cselect_b32 s53, s41, s51
	s_cselect_b32 s52, s47, s50
	s_cselect_b32 s51, s39, s75
	s_cselect_b32 s50, s73, s74
	s_add_i32 m0, s21, 0xc000
	ds_read_b128 v[146:149], v241
	ds_read_b128 v[150:153], v241 offset:1024
	ds_read_b128 v[154:157], v241 offset:2048
	ds_read_b128 v[158:161], v241 offset:3072
	ds_read_b128 v[176:179], v241 offset:4096
	ds_read_b128 v[180:183], v241 offset:5120
	ds_read_b128 v[184:187], v241 offset:6144
	ds_read_b128 v[188:191], v241 offset:7168
	global_load_lds_dwordx4 v166, s[48:49]
	s_add_i32 m0, s21, 0xe000
	s_nop 0
	global_load_lds_dwordx4 v170, s[48:49]
	s_waitcnt vmcnt(10)
	s_waitcnt lgkmcnt(8)
	s_barrier
	s_waitcnt lgkmcnt(0)
	s_setprio 1
	s_waitcnt lgkmcnt(0)
	v_mfma_f32_16x16x32_bf16 v[126:129], v[130:133], v[146:149], 0
	v_mfma_f32_16x16x32_bf16 v[122:125], v[138:141], v[146:149], 0
	v_mfma_f32_16x16x32_bf16 v[118:121], v[130:133], v[154:157], 0
	v_mfma_f32_16x16x32_bf16 v[114:117], v[138:141], v[154:157], 0
	v_mfma_f32_16x16x32_bf16 v[106:109], v[130:133], v[176:179], 0
	v_mfma_f32_16x16x32_bf16 v[98:101], v[138:141], v[176:179], 0
	v_mfma_f32_16x16x32_bf16 v[90:93], v[130:133], v[184:187], 0
	v_mfma_f32_16x16x32_bf16 v[82:85], v[138:141], v[184:187], 0
	v_mfma_f32_16x16x32_bf16 v[126:129], v[134:137], v[150:153], v[126:129]
	v_mfma_f32_16x16x32_bf16 v[122:125], v[142:145], v[150:153], v[122:125]
	v_mfma_f32_16x16x32_bf16 v[118:121], v[134:137], v[158:161], v[118:121]
	v_mfma_f32_16x16x32_bf16 v[114:117], v[142:145], v[158:161], v[114:117]
	v_mfma_f32_16x16x32_bf16 v[106:109], v[134:137], v[180:183], v[106:109]
	v_mfma_f32_16x16x32_bf16 v[98:101], v[142:145], v[180:183], v[98:101]
	v_mfma_f32_16x16x32_bf16 v[90:93], v[134:137], v[188:191], v[90:93]
	v_mfma_f32_16x16x32_bf16 v[82:85], v[142:145], v[188:191], v[82:85]
	s_setprio 0
	s_barrier
	s_add_i32 s81, s68, s56
	s_add_u32 s96, s50, 0x80
	s_addc_u32 s97, s51, 0
	s_mov_b32 m0, s81
	ds_read_b128 v[192:195], v242
	ds_read_b128 v[196:199], v242 offset:1024
	ds_read_b128 v[200:203], v242 offset:2048
	ds_read_b128 v[204:207], v242 offset:3072
	global_load_lds_dwordx4 v162, s[50:51]
	s_add_i32 m0, s81, 0x2000
	s_nop 0
	global_load_lds_dwordx4 v164, s[50:51]
	s_waitcnt vmcnt(10)
	s_barrier
	s_waitcnt lgkmcnt(0)
	s_setprio 1
	s_waitcnt lgkmcnt(0)
	v_mfma_f32_16x16x32_bf16 v[110:113], v[192:195], v[146:149], 0
	v_mfma_f32_16x16x32_bf16 v[102:105], v[200:203], v[146:149], 0
	v_mfma_f32_16x16x32_bf16 v[94:97], v[192:195], v[154:157], 0
	v_mfma_f32_16x16x32_bf16 v[86:89], v[200:203], v[154:157], 0
	v_mfma_f32_16x16x32_bf16 v[78:81], v[192:195], v[176:179], 0
	v_mfma_f32_16x16x32_bf16 v[74:77], v[200:203], v[176:179], 0
	v_mfma_f32_16x16x32_bf16 v[70:73], v[192:195], v[184:187], 0
	v_mfma_f32_16x16x32_bf16 v[66:69], v[200:203], v[184:187], 0
	v_mfma_f32_16x16x32_bf16 v[110:113], v[196:199], v[150:153], v[110:113]
	v_mfma_f32_16x16x32_bf16 v[102:105], v[204:207], v[150:153], v[102:105]
	v_mfma_f32_16x16x32_bf16 v[94:97], v[196:199], v[158:161], v[94:97]
	v_mfma_f32_16x16x32_bf16 v[86:89], v[204:207], v[158:161], v[86:89]
	v_mfma_f32_16x16x32_bf16 v[78:81], v[196:199], v[180:183], v[78:81]
	v_mfma_f32_16x16x32_bf16 v[74:77], v[204:207], v[180:183], v[74:77]
	v_mfma_f32_16x16x32_bf16 v[70:73], v[196:199], v[188:191], v[70:73]
	v_mfma_f32_16x16x32_bf16 v[66:69], v[204:207], v[188:191], v[66:69]
	s_setprio 0
	s_mov_b32 m0, s21
	s_add_u32 s94, s52, 0x80
	s_addc_u32 s95, s53, 0
	s_barrier
	ds_read_b128 v[146:149], v241 offset:16384
	ds_read_b128 v[150:153], v241 offset:17408
	ds_read_b128 v[154:157], v241 offset:18432
	ds_read_b128 v[158:161], v241 offset:19456
	ds_read_b128 v[176:179], v241 offset:20480
	ds_read_b128 v[180:183], v241 offset:21504
	ds_read_b128 v[184:187], v241 offset:22528
	ds_read_b128 v[188:191], v241 offset:23552
	global_load_lds_dwordx4 v162, s[52:53]
	s_mov_b32 m0, s59
	s_nop 0
	global_load_lds_dwordx4 v164, s[52:53]
	s_waitcnt vmcnt(10)
	s_barrier
	s_waitcnt lgkmcnt(0)
	s_setprio 1
	s_waitcnt lgkmcnt(0)
	v_mfma_f32_16x16x32_bf16 v[62:65], v[130:133], v[146:149], 0
	v_mfma_f32_16x16x32_bf16 v[58:61], v[138:141], v[146:149], 0
	v_mfma_f32_16x16x32_bf16 v[54:57], v[130:133], v[154:157], 0
	v_mfma_f32_16x16x32_bf16 v[50:53], v[138:141], v[154:157], 0
	v_mfma_f32_16x16x32_bf16 v[42:45], v[130:133], v[176:179], 0
	v_mfma_f32_16x16x32_bf16 v[34:37], v[138:141], v[176:179], 0
	v_mfma_f32_16x16x32_bf16 v[26:29], v[130:133], v[184:187], 0
	v_mfma_f32_16x16x32_bf16 v[18:21], v[138:141], v[184:187], 0
	v_mfma_f32_16x16x32_bf16 v[62:65], v[134:137], v[150:153], v[62:65]
	v_mfma_f32_16x16x32_bf16 v[58:61], v[142:145], v[150:153], v[58:61]
	v_mfma_f32_16x16x32_bf16 v[54:57], v[134:137], v[158:161], v[54:57]
	v_mfma_f32_16x16x32_bf16 v[50:53], v[142:145], v[158:161], v[50:53]
	v_mfma_f32_16x16x32_bf16 v[42:45], v[134:137], v[180:183], v[42:45]
	v_mfma_f32_16x16x32_bf16 v[34:37], v[142:145], v[180:183], v[34:37]
	v_mfma_f32_16x16x32_bf16 v[26:29], v[134:137], v[188:191], v[26:29]
	v_mfma_f32_16x16x32_bf16 v[18:21], v[142:145], v[188:191], v[18:21]
	s_setprio 0
	s_barrier
	s_add_u32 s82, s50, 0x80000
	s_addc_u32 s83, s51, 0
	s_add_i32 s81, s69, s56
	s_mov_b32 m0, s81
	s_nop 0
	global_load_lds_dwordx4 v162, s[82:83]
	s_add_i32 m0, s81, 0x2000
	s_nop 0
	global_load_lds_dwordx4 v164, s[82:83]
	s_waitcnt vmcnt(10)
	s_barrier
	s_setprio 1
	v_mfma_f32_16x16x32_bf16 v[46:49], v[192:195], v[146:149], 0
	v_mfma_f32_16x16x32_bf16 v[38:41], v[200:203], v[146:149], 0
	v_mfma_f32_16x16x32_bf16 v[30:33], v[192:195], v[154:157], 0
	v_mfma_f32_16x16x32_bf16 v[22:25], v[200:203], v[154:157], 0
	v_mfma_f32_16x16x32_bf16 v[14:17], v[192:195], v[176:179], 0
	v_mfma_f32_16x16x32_bf16 v[10:13], v[200:203], v[176:179], 0
	v_mfma_f32_16x16x32_bf16 v[6:9], v[192:195], v[184:187], 0
	v_mfma_f32_16x16x32_bf16 v[2:5], v[200:203], v[184:187], 0
	v_mfma_f32_16x16x32_bf16 v[46:49], v[196:199], v[150:153], v[46:49]
	v_mfma_f32_16x16x32_bf16 v[38:41], v[204:207], v[150:153], v[38:41]
	v_mfma_f32_16x16x32_bf16 v[30:33], v[196:199], v[158:161], v[30:33]
	v_mfma_f32_16x16x32_bf16 v[22:25], v[204:207], v[158:161], v[22:25]
	v_mfma_f32_16x16x32_bf16 v[14:17], v[196:199], v[180:183], v[14:17]
	v_mfma_f32_16x16x32_bf16 v[10:13], v[204:207], v[180:183], v[10:13]
	v_mfma_f32_16x16x32_bf16 v[6:9], v[196:199], v[188:191], v[6:9]
	v_mfma_f32_16x16x32_bf16 v[2:5], v[204:207], v[188:191], v[2:5]
	s_setprio 0
	s_add_i32 s81, 0, 0x18000
	v_add_u32_e32 v142, s81, v236
	s_barrier
	ds_read_b128 v[130:133], v142
	ds_read_b128 v[134:137], v142 offset:1024
	ds_read_b128 v[138:141], v142 offset:2048
	ds_read_b128 v[142:145], v142 offset:3072
	s_add_u32 s52, s52, 0x80000
	s_addc_u32 s53, s53, 0
	s_mov_b32 m0, s60
	ds_read_b128 v[146:149], v241 offset:32768
	ds_read_b128 v[150:153], v241 offset:33792
	ds_read_b128 v[154:157], v241 offset:34816
	ds_read_b128 v[158:161], v241 offset:35840
	ds_read_b128 v[176:179], v241 offset:36864
	ds_read_b128 v[180:183], v241 offset:37888
	ds_read_b128 v[184:187], v241 offset:38912
	ds_read_b128 v[188:191], v241 offset:39936
	global_load_lds_dwordx4 v162, s[52:53]
	s_mov_b32 m0, s61
	s_nop 0
	global_load_lds_dwordx4 v164, s[52:53]
	s_waitcnt vmcnt(10)
	s_waitcnt lgkmcnt(8)
	s_barrier
	s_waitcnt lgkmcnt(0)
	s_setprio 1
	s_waitcnt lgkmcnt(0)
	v_mfma_f32_16x16x32_bf16 v[126:129], v[130:133], v[146:149], v[126:129]
	v_mfma_f32_16x16x32_bf16 v[122:125], v[138:141], v[146:149], v[122:125]
	v_mfma_f32_16x16x32_bf16 v[118:121], v[130:133], v[154:157], v[118:121]
	v_mfma_f32_16x16x32_bf16 v[114:117], v[138:141], v[154:157], v[114:117]
	v_mfma_f32_16x16x32_bf16 v[106:109], v[130:133], v[176:179], v[106:109]
	v_mfma_f32_16x16x32_bf16 v[98:101], v[138:141], v[176:179], v[98:101]
	v_mfma_f32_16x16x32_bf16 v[90:93], v[130:133], v[184:187], v[90:93]
	v_mfma_f32_16x16x32_bf16 v[82:85], v[138:141], v[184:187], v[82:85]
	v_mfma_f32_16x16x32_bf16 v[126:129], v[134:137], v[150:153], v[126:129]
	v_mfma_f32_16x16x32_bf16 v[122:125], v[142:145], v[150:153], v[122:125]
	v_mfma_f32_16x16x32_bf16 v[118:121], v[134:137], v[158:161], v[118:121]
	v_mfma_f32_16x16x32_bf16 v[114:117], v[142:145], v[158:161], v[114:117]
	v_mfma_f32_16x16x32_bf16 v[106:109], v[134:137], v[180:183], v[106:109]
	v_mfma_f32_16x16x32_bf16 v[98:101], v[142:145], v[180:183], v[98:101]
	v_mfma_f32_16x16x32_bf16 v[90:93], v[134:137], v[188:191], v[90:93]
	v_mfma_f32_16x16x32_bf16 v[82:85], v[142:145], v[188:191], v[82:85]
	s_setprio 0
	s_barrier
	s_add_i32 s52, 0, 0x1c000
	s_add_i32 s53, s81, s56
	v_add_u32_e32 v204, s52, v236
	s_mov_b32 m0, s53
	ds_read_b128 v[192:195], v204
	ds_read_b128 v[196:199], v204 offset:1024
	ds_read_b128 v[200:203], v204 offset:2048
	ds_read_b128 v[204:207], v204 offset:3072
	global_load_lds_dwordx4 v162, s[96:97]
	s_add_i32 m0, s53, 0x2000
	s_nop 0
	global_load_lds_dwordx4 v164, s[96:97]
	s_waitcnt vmcnt(10)
	s_barrier
	s_waitcnt lgkmcnt(0)
	s_setprio 1
	s_waitcnt lgkmcnt(0)
	v_mfma_f32_16x16x32_bf16 v[110:113], v[192:195], v[146:149], v[110:113]
	v_mfma_f32_16x16x32_bf16 v[102:105], v[200:203], v[146:149], v[102:105]
	v_mfma_f32_16x16x32_bf16 v[94:97], v[192:195], v[154:157], v[94:97]
	v_mfma_f32_16x16x32_bf16 v[86:89], v[200:203], v[154:157], v[86:89]
	v_mfma_f32_16x16x32_bf16 v[78:81], v[192:195], v[176:179], v[78:81]
	v_mfma_f32_16x16x32_bf16 v[74:77], v[200:203], v[176:179], v[74:77]
	v_mfma_f32_16x16x32_bf16 v[70:73], v[192:195], v[184:187], v[70:73]
	v_mfma_f32_16x16x32_bf16 v[66:69], v[200:203], v[184:187], v[66:69]
	v_mfma_f32_16x16x32_bf16 v[110:113], v[196:199], v[150:153], v[110:113]
	v_mfma_f32_16x16x32_bf16 v[102:105], v[204:207], v[150:153], v[102:105]
	v_mfma_f32_16x16x32_bf16 v[94:97], v[196:199], v[158:161], v[94:97]
	v_mfma_f32_16x16x32_bf16 v[86:89], v[204:207], v[158:161], v[86:89]
	v_mfma_f32_16x16x32_bf16 v[78:81], v[196:199], v[180:183], v[78:81]
	v_mfma_f32_16x16x32_bf16 v[74:77], v[204:207], v[180:183], v[74:77]
	v_mfma_f32_16x16x32_bf16 v[70:73], v[196:199], v[188:191], v[70:73]
	v_mfma_f32_16x16x32_bf16 v[66:69], v[204:207], v[188:191], v[66:69]
	s_setprio 0
	s_mov_b32 m0, s64
	s_barrier
	ds_read_b128 v[146:149], v241 offset:49152
	ds_read_b128 v[150:153], v241 offset:50176
	ds_read_b128 v[154:157], v241 offset:51200
	ds_read_b128 v[158:161], v241 offset:52224
	ds_read_b128 v[176:179], v241 offset:53248
	ds_read_b128 v[180:183], v241 offset:54272
	ds_read_b128 v[184:187], v241 offset:55296
	ds_read_b128 v[188:191], v241 offset:56320
	global_load_lds_dwordx4 v162, s[94:95]
	s_mov_b32 m0, s65
	s_nop 0
	global_load_lds_dwordx4 v164, s[94:95]
	s_waitcnt vmcnt(10)
	s_barrier
	s_waitcnt lgkmcnt(0)
	s_setprio 1
	s_waitcnt lgkmcnt(0)
	v_mfma_f32_16x16x32_bf16 v[62:65], v[130:133], v[146:149], v[62:65]
	v_mfma_f32_16x16x32_bf16 v[58:61], v[138:141], v[146:149], v[58:61]
	v_mfma_f32_16x16x32_bf16 v[54:57], v[130:133], v[154:157], v[54:57]
	v_mfma_f32_16x16x32_bf16 v[50:53], v[138:141], v[154:157], v[50:53]
	v_mfma_f32_16x16x32_bf16 v[42:45], v[130:133], v[176:179], v[42:45]
	v_mfma_f32_16x16x32_bf16 v[34:37], v[138:141], v[176:179], v[34:37]
	v_mfma_f32_16x16x32_bf16 v[26:29], v[130:133], v[184:187], v[26:29]
	v_mfma_f32_16x16x32_bf16 v[18:21], v[138:141], v[184:187], v[18:21]
	v_mfma_f32_16x16x32_bf16 v[62:65], v[134:137], v[150:153], v[62:65]
	v_mfma_f32_16x16x32_bf16 v[58:61], v[142:145], v[150:153], v[58:61]
	v_mfma_f32_16x16x32_bf16 v[54:57], v[134:137], v[158:161], v[54:57]
	v_mfma_f32_16x16x32_bf16 v[50:53], v[142:145], v[158:161], v[50:53]
	v_mfma_f32_16x16x32_bf16 v[42:45], v[134:137], v[180:183], v[42:45]
	v_mfma_f32_16x16x32_bf16 v[34:37], v[142:145], v[180:183], v[34:37]
	v_mfma_f32_16x16x32_bf16 v[26:29], v[134:137], v[188:191], v[26:29]
	v_mfma_f32_16x16x32_bf16 v[18:21], v[142:145], v[188:191], v[18:21]
	s_setprio 0
	s_barrier
	s_add_u32 s50, s50, 0x80080
	s_addc_u32 s51, s51, 0
	s_add_i32 s52, s52, s56
	s_mov_b32 m0, s52
	s_nop 0
	global_load_lds_dwordx4 v162, s[50:51]
	s_add_i32 m0, s52, 0x2000
	s_nop 0
	global_load_lds_dwordx4 v164, s[50:51]
	s_waitcnt vmcnt(10)
	s_barrier
	s_setprio 1
	v_mfma_f32_16x16x32_bf16 v[46:49], v[192:195], v[146:149], v[46:49]
	v_mfma_f32_16x16x32_bf16 v[38:41], v[200:203], v[146:149], v[38:41]
	v_mfma_f32_16x16x32_bf16 v[30:33], v[192:195], v[154:157], v[30:33]
	v_mfma_f32_16x16x32_bf16 v[22:25], v[200:203], v[154:157], v[22:25]
	v_mfma_f32_16x16x32_bf16 v[14:17], v[192:195], v[176:179], v[14:17]
	v_mfma_f32_16x16x32_bf16 v[10:13], v[200:203], v[176:179], v[10:13]
	v_mfma_f32_16x16x32_bf16 v[6:9], v[192:195], v[184:187], v[6:9]
	v_mfma_f32_16x16x32_bf16 v[2:5], v[200:203], v[184:187], v[2:5]
	v_mfma_f32_16x16x32_bf16 v[46:49], v[196:199], v[150:153], v[46:49]
	v_mfma_f32_16x16x32_bf16 v[38:41], v[204:207], v[150:153], v[38:41]
	v_mfma_f32_16x16x32_bf16 v[30:33], v[196:199], v[158:161], v[30:33]
	v_mfma_f32_16x16x32_bf16 v[22:25], v[204:207], v[158:161], v[22:25]
	v_mfma_f32_16x16x32_bf16 v[14:17], v[196:199], v[180:183], v[14:17]
	v_mfma_f32_16x16x32_bf16 v[10:13], v[204:207], v[180:183], v[10:13]
	v_mfma_f32_16x16x32_bf16 v[6:9], v[196:199], v[188:191], v[6:9]
	v_mfma_f32_16x16x32_bf16 v[2:5], v[204:207], v[188:191], v[2:5]
	s_setprio 0
	s_add_i32 s80, s80, 2
	s_add_u32 s48, s48, 0x100
	s_addc_u32 s49, s49, 0
	s_add_u32 s74, s74, 0x100
	s_addc_u32 s75, s75, 0
	s_cmp_gt_u32 s80, s87
	s_barrier
	s_cbranch_scc0 .LBB0_1098
	s_branch .Lp8_loop_exit
.LBB0_1098:
	ds_read_b128 v[130:133], v240
	ds_read_b128 v[134:137], v240 offset:1024
	ds_read_b128 v[138:141], v240 offset:2048
	ds_read_b128 v[142:145], v240 offset:3072
	s_add_u32 s50, s48, 0xfff80080
	s_addc_u32 s51, s49, -1
	s_cmp_eq_u32 s80, s87
	s_cselect_b32 s53, s41, s51
	s_cselect_b32 s52, s47, s50
	s_cselect_b32 s51, s39, s75
	s_cselect_b32 s50, s73, s74
	s_add_i32 m0, s21, 0xc000
	ds_read_b128 v[146:149], v241
	ds_read_b128 v[150:153], v241 offset:1024
	ds_read_b128 v[154:157], v241 offset:2048
	ds_read_b128 v[158:161], v241 offset:3072
	ds_read_b128 v[176:179], v241 offset:4096
	ds_read_b128 v[180:183], v241 offset:5120
	ds_read_b128 v[184:187], v241 offset:6144
	ds_read_b128 v[188:191], v241 offset:7168
	global_load_lds_dwordx4 v166, s[48:49]
	s_add_i32 m0, s21, 0xe000
	s_nop 0
	global_load_lds_dwordx4 v170, s[48:49]
	s_waitcnt vmcnt(10)
	s_waitcnt lgkmcnt(8)
	s_barrier
	s_waitcnt lgkmcnt(0)
	s_setprio 1
	s_waitcnt lgkmcnt(0)
	v_mfma_f32_16x16x32_bf16 v[126:129], v[130:133], v[146:149], v[126:129]
	v_mfma_f32_16x16x32_bf16 v[122:125], v[138:141], v[146:149], v[122:125]
	v_mfma_f32_16x16x32_bf16 v[118:121], v[130:133], v[154:157], v[118:121]
	v_mfma_f32_16x16x32_bf16 v[114:117], v[138:141], v[154:157], v[114:117]
	v_mfma_f32_16x16x32_bf16 v[106:109], v[130:133], v[176:179], v[106:109]
	v_mfma_f32_16x16x32_bf16 v[98:101], v[138:141], v[176:179], v[98:101]
	v_mfma_f32_16x16x32_bf16 v[90:93], v[130:133], v[184:187], v[90:93]
	v_mfma_f32_16x16x32_bf16 v[82:85], v[138:141], v[184:187], v[82:85]
	v_mfma_f32_16x16x32_bf16 v[126:129], v[134:137], v[150:153], v[126:129]
	v_mfma_f32_16x16x32_bf16 v[122:125], v[142:145], v[150:153], v[122:125]
	v_mfma_f32_16x16x32_bf16 v[118:121], v[134:137], v[158:161], v[118:121]
	v_mfma_f32_16x16x32_bf16 v[114:117], v[142:145], v[158:161], v[114:117]
	v_mfma_f32_16x16x32_bf16 v[106:109], v[134:137], v[180:183], v[106:109]
	v_mfma_f32_16x16x32_bf16 v[98:101], v[142:145], v[180:183], v[98:101]
	v_mfma_f32_16x16x32_bf16 v[90:93], v[134:137], v[188:191], v[90:93]
	v_mfma_f32_16x16x32_bf16 v[82:85], v[142:145], v[188:191], v[82:85]
	s_setprio 0
	s_barrier
	s_add_i32 s81, s68, s56
	s_add_u32 s96, s50, 0x80
	s_addc_u32 s97, s51, 0
	s_mov_b32 m0, s81
	ds_read_b128 v[192:195], v242
	ds_read_b128 v[196:199], v242 offset:1024
	ds_read_b128 v[200:203], v242 offset:2048
	ds_read_b128 v[204:207], v242 offset:3072
	global_load_lds_dwordx4 v162, s[50:51]
	s_add_i32 m0, s81, 0x2000
	s_nop 0
	global_load_lds_dwordx4 v164, s[50:51]
	s_waitcnt vmcnt(10)
	s_barrier
	s_waitcnt lgkmcnt(0)
	s_setprio 1
	s_waitcnt lgkmcnt(0)
	v_mfma_f32_16x16x32_bf16 v[110:113], v[192:195], v[146:149], v[110:113]
	v_mfma_f32_16x16x32_bf16 v[102:105], v[200:203], v[146:149], v[102:105]
	v_mfma_f32_16x16x32_bf16 v[94:97], v[192:195], v[154:157], v[94:97]
	v_mfma_f32_16x16x32_bf16 v[86:89], v[200:203], v[154:157], v[86:89]
	v_mfma_f32_16x16x32_bf16 v[78:81], v[192:195], v[176:179], v[78:81]
	v_mfma_f32_16x16x32_bf16 v[74:77], v[200:203], v[176:179], v[74:77]
	v_mfma_f32_16x16x32_bf16 v[70:73], v[192:195], v[184:187], v[70:73]
	v_mfma_f32_16x16x32_bf16 v[66:69], v[200:203], v[184:187], v[66:69]
	v_mfma_f32_16x16x32_bf16 v[110:113], v[196:199], v[150:153], v[110:113]
	v_mfma_f32_16x16x32_bf16 v[102:105], v[204:207], v[150:153], v[102:105]
	v_mfma_f32_16x16x32_bf16 v[94:97], v[196:199], v[158:161], v[94:97]
	v_mfma_f32_16x16x32_bf16 v[86:89], v[204:207], v[158:161], v[86:89]
	v_mfma_f32_16x16x32_bf16 v[78:81], v[196:199], v[180:183], v[78:81]
	v_mfma_f32_16x16x32_bf16 v[74:77], v[204:207], v[180:183], v[74:77]
	v_mfma_f32_16x16x32_bf16 v[70:73], v[196:199], v[188:191], v[70:73]
	v_mfma_f32_16x16x32_bf16 v[66:69], v[204:207], v[188:191], v[66:69]
	s_setprio 0
	s_mov_b32 m0, s21
	s_add_u32 s94, s52, 0x80
	s_addc_u32 s95, s53, 0
	s_barrier
	ds_read_b128 v[146:149], v241 offset:16384
	ds_read_b128 v[150:153], v241 offset:17408
	ds_read_b128 v[154:157], v241 offset:18432
	ds_read_b128 v[158:161], v241 offset:19456
	ds_read_b128 v[176:179], v241 offset:20480
	ds_read_b128 v[180:183], v241 offset:21504
	ds_read_b128 v[184:187], v241 offset:22528
	ds_read_b128 v[188:191], v241 offset:23552
	global_load_lds_dwordx4 v162, s[52:53]
	s_mov_b32 m0, s59
	s_nop 0
	global_load_lds_dwordx4 v164, s[52:53]
	s_waitcnt vmcnt(10)
	s_barrier
	s_waitcnt lgkmcnt(0)
	s_setprio 1
	s_waitcnt lgkmcnt(0)
	v_mfma_f32_16x16x32_bf16 v[62:65], v[130:133], v[146:149], v[62:65]
	v_mfma_f32_16x16x32_bf16 v[58:61], v[138:141], v[146:149], v[58:61]
	v_mfma_f32_16x16x32_bf16 v[54:57], v[130:133], v[154:157], v[54:57]
	v_mfma_f32_16x16x32_bf16 v[50:53], v[138:141], v[154:157], v[50:53]
	v_mfma_f32_16x16x32_bf16 v[42:45], v[130:133], v[176:179], v[42:45]
	v_mfma_f32_16x16x32_bf16 v[34:37], v[138:141], v[176:179], v[34:37]
	v_mfma_f32_16x16x32_bf16 v[26:29], v[130:133], v[184:187], v[26:29]
	v_mfma_f32_16x16x32_bf16 v[18:21], v[138:141], v[184:187], v[18:21]
	v_mfma_f32_16x16x32_bf16 v[62:65], v[134:137], v[150:153], v[62:65]
	v_mfma_f32_16x16x32_bf16 v[58:61], v[142:145], v[150:153], v[58:61]
	v_mfma_f32_16x16x32_bf16 v[54:57], v[134:137], v[158:161], v[54:57]
	v_mfma_f32_16x16x32_bf16 v[50:53], v[142:145], v[158:161], v[50:53]
	v_mfma_f32_16x16x32_bf16 v[42:45], v[134:137], v[180:183], v[42:45]
	v_mfma_f32_16x16x32_bf16 v[34:37], v[142:145], v[180:183], v[34:37]
	v_mfma_f32_16x16x32_bf16 v[26:29], v[134:137], v[188:191], v[26:29]
	v_mfma_f32_16x16x32_bf16 v[18:21], v[142:145], v[188:191], v[18:21]
	s_setprio 0
	s_barrier
	s_add_u32 s82, s50, 0x80000
	s_addc_u32 s83, s51, 0
	s_add_i32 s81, s69, s56
	s_mov_b32 m0, s81
	s_nop 0
	global_load_lds_dwordx4 v162, s[82:83]
	s_add_i32 m0, s81, 0x2000
	s_nop 0
	global_load_lds_dwordx4 v164, s[82:83]
	s_waitcnt vmcnt(10)
	s_barrier
	s_setprio 1
	v_mfma_f32_16x16x32_bf16 v[46:49], v[192:195], v[146:149], v[46:49]
	v_mfma_f32_16x16x32_bf16 v[38:41], v[200:203], v[146:149], v[38:41]
	v_mfma_f32_16x16x32_bf16 v[30:33], v[192:195], v[154:157], v[30:33]
	v_mfma_f32_16x16x32_bf16 v[22:25], v[200:203], v[154:157], v[22:25]
	v_mfma_f32_16x16x32_bf16 v[14:17], v[192:195], v[176:179], v[14:17]
	v_mfma_f32_16x16x32_bf16 v[10:13], v[200:203], v[176:179], v[10:13]
	v_mfma_f32_16x16x32_bf16 v[6:9], v[192:195], v[184:187], v[6:9]
	v_mfma_f32_16x16x32_bf16 v[2:5], v[200:203], v[184:187], v[2:5]
	v_mfma_f32_16x16x32_bf16 v[46:49], v[196:199], v[150:153], v[46:49]
	v_mfma_f32_16x16x32_bf16 v[38:41], v[204:207], v[150:153], v[38:41]
	v_mfma_f32_16x16x32_bf16 v[30:33], v[196:199], v[158:161], v[30:33]
	v_mfma_f32_16x16x32_bf16 v[22:25], v[204:207], v[158:161], v[22:25]
	v_mfma_f32_16x16x32_bf16 v[14:17], v[196:199], v[180:183], v[14:17]
	v_mfma_f32_16x16x32_bf16 v[10:13], v[204:207], v[180:183], v[10:13]
	v_mfma_f32_16x16x32_bf16 v[6:9], v[196:199], v[188:191], v[6:9]
	v_mfma_f32_16x16x32_bf16 v[2:5], v[204:207], v[188:191], v[2:5]
	s_setprio 0
	s_add_i32 s81, 0, 0x18000
	v_add_u32_e32 v142, s81, v236
	s_barrier
	ds_read_b128 v[130:133], v142
	ds_read_b128 v[134:137], v142 offset:1024
	ds_read_b128 v[138:141], v142 offset:2048
	ds_read_b128 v[142:145], v142 offset:3072
	s_add_u32 s52, s52, 0x80000
	s_addc_u32 s53, s53, 0
	s_mov_b32 m0, s60
	ds_read_b128 v[146:149], v241 offset:32768
	ds_read_b128 v[150:153], v241 offset:33792
	ds_read_b128 v[154:157], v241 offset:34816
	ds_read_b128 v[158:161], v241 offset:35840
	ds_read_b128 v[176:179], v241 offset:36864
	ds_read_b128 v[180:183], v241 offset:37888
	ds_read_b128 v[184:187], v241 offset:38912
	ds_read_b128 v[188:191], v241 offset:39936
	global_load_lds_dwordx4 v162, s[52:53]
	s_mov_b32 m0, s61
	s_nop 0
	global_load_lds_dwordx4 v164, s[52:53]
	s_waitcnt vmcnt(10)
	s_waitcnt lgkmcnt(8)
	s_barrier
	s_waitcnt lgkmcnt(0)
	s_setprio 1
	s_waitcnt lgkmcnt(0)
	v_mfma_f32_16x16x32_bf16 v[126:129], v[130:133], v[146:149], v[126:129]
	v_mfma_f32_16x16x32_bf16 v[122:125], v[138:141], v[146:149], v[122:125]
	v_mfma_f32_16x16x32_bf16 v[118:121], v[130:133], v[154:157], v[118:121]
	v_mfma_f32_16x16x32_bf16 v[114:117], v[138:141], v[154:157], v[114:117]
	v_mfma_f32_16x16x32_bf16 v[106:109], v[130:133], v[176:179], v[106:109]
	v_mfma_f32_16x16x32_bf16 v[98:101], v[138:141], v[176:179], v[98:101]
	v_mfma_f32_16x16x32_bf16 v[90:93], v[130:133], v[184:187], v[90:93]
	v_mfma_f32_16x16x32_bf16 v[82:85], v[138:141], v[184:187], v[82:85]
	v_mfma_f32_16x16x32_bf16 v[126:129], v[134:137], v[150:153], v[126:129]
	v_mfma_f32_16x16x32_bf16 v[122:125], v[142:145], v[150:153], v[122:125]
	v_mfma_f32_16x16x32_bf16 v[118:121], v[134:137], v[158:161], v[118:121]
	v_mfma_f32_16x16x32_bf16 v[114:117], v[142:145], v[158:161], v[114:117]
	v_mfma_f32_16x16x32_bf16 v[106:109], v[134:137], v[180:183], v[106:109]
	v_mfma_f32_16x16x32_bf16 v[98:101], v[142:145], v[180:183], v[98:101]
	v_mfma_f32_16x16x32_bf16 v[90:93], v[134:137], v[188:191], v[90:93]
	v_mfma_f32_16x16x32_bf16 v[82:85], v[142:145], v[188:191], v[82:85]
	s_setprio 0
	s_barrier
	s_add_i32 s52, 0, 0x1c000
	s_add_i32 s53, s81, s56
	v_add_u32_e32 v204, s52, v236
	s_mov_b32 m0, s53
	ds_read_b128 v[192:195], v204
	ds_read_b128 v[196:199], v204 offset:1024
	ds_read_b128 v[200:203], v204 offset:2048
	ds_read_b128 v[204:207], v204 offset:3072
	global_load_lds_dwordx4 v162, s[96:97]
	s_add_i32 m0, s53, 0x2000
	s_nop 0
	global_load_lds_dwordx4 v164, s[96:97]
	s_waitcnt vmcnt(10)
	s_barrier
	s_waitcnt lgkmcnt(0)
	s_setprio 1
	s_waitcnt lgkmcnt(0)
	v_mfma_f32_16x16x32_bf16 v[110:113], v[192:195], v[146:149], v[110:113]
	v_mfma_f32_16x16x32_bf16 v[102:105], v[200:203], v[146:149], v[102:105]
	v_mfma_f32_16x16x32_bf16 v[94:97], v[192:195], v[154:157], v[94:97]
	v_mfma_f32_16x16x32_bf16 v[86:89], v[200:203], v[154:157], v[86:89]
	v_mfma_f32_16x16x32_bf16 v[78:81], v[192:195], v[176:179], v[78:81]
	v_mfma_f32_16x16x32_bf16 v[74:77], v[200:203], v[176:179], v[74:77]
	v_mfma_f32_16x16x32_bf16 v[70:73], v[192:195], v[184:187], v[70:73]
	v_mfma_f32_16x16x32_bf16 v[66:69], v[200:203], v[184:187], v[66:69]
	v_mfma_f32_16x16x32_bf16 v[110:113], v[196:199], v[150:153], v[110:113]
	v_mfma_f32_16x16x32_bf16 v[102:105], v[204:207], v[150:153], v[102:105]
	v_mfma_f32_16x16x32_bf16 v[94:97], v[196:199], v[158:161], v[94:97]
	v_mfma_f32_16x16x32_bf16 v[86:89], v[204:207], v[158:161], v[86:89]
	v_mfma_f32_16x16x32_bf16 v[78:81], v[196:199], v[180:183], v[78:81]
	v_mfma_f32_16x16x32_bf16 v[74:77], v[204:207], v[180:183], v[74:77]
	v_mfma_f32_16x16x32_bf16 v[70:73], v[196:199], v[188:191], v[70:73]
	v_mfma_f32_16x16x32_bf16 v[66:69], v[204:207], v[188:191], v[66:69]
	s_setprio 0
	s_mov_b32 m0, s64
	s_barrier
	ds_read_b128 v[146:149], v241 offset:49152
	ds_read_b128 v[150:153], v241 offset:50176
	ds_read_b128 v[154:157], v241 offset:51200
	ds_read_b128 v[158:161], v241 offset:52224
	ds_read_b128 v[176:179], v241 offset:53248
	ds_read_b128 v[180:183], v241 offset:54272
	ds_read_b128 v[184:187], v241 offset:55296
	ds_read_b128 v[188:191], v241 offset:56320
	global_load_lds_dwordx4 v162, s[94:95]
	s_mov_b32 m0, s65
	s_nop 0
	global_load_lds_dwordx4 v164, s[94:95]
	s_waitcnt vmcnt(10)
	s_barrier
	s_waitcnt lgkmcnt(0)
	s_setprio 1
	s_waitcnt lgkmcnt(0)
	v_mfma_f32_16x16x32_bf16 v[62:65], v[130:133], v[146:149], v[62:65]
	v_mfma_f32_16x16x32_bf16 v[58:61], v[138:141], v[146:149], v[58:61]
	v_mfma_f32_16x16x32_bf16 v[54:57], v[130:133], v[154:157], v[54:57]
	v_mfma_f32_16x16x32_bf16 v[50:53], v[138:141], v[154:157], v[50:53]
	v_mfma_f32_16x16x32_bf16 v[42:45], v[130:133], v[176:179], v[42:45]
	v_mfma_f32_16x16x32_bf16 v[34:37], v[138:141], v[176:179], v[34:37]
	v_mfma_f32_16x16x32_bf16 v[26:29], v[130:133], v[184:187], v[26:29]
	v_mfma_f32_16x16x32_bf16 v[18:21], v[138:141], v[184:187], v[18:21]
	v_mfma_f32_16x16x32_bf16 v[62:65], v[134:137], v[150:153], v[62:65]
	v_mfma_f32_16x16x32_bf16 v[58:61], v[142:145], v[150:153], v[58:61]
	v_mfma_f32_16x16x32_bf16 v[54:57], v[134:137], v[158:161], v[54:57]
	v_mfma_f32_16x16x32_bf16 v[50:53], v[142:145], v[158:161], v[50:53]
	v_mfma_f32_16x16x32_bf16 v[42:45], v[134:137], v[180:183], v[42:45]
	v_mfma_f32_16x16x32_bf16 v[34:37], v[142:145], v[180:183], v[34:37]
	v_mfma_f32_16x16x32_bf16 v[26:29], v[134:137], v[188:191], v[26:29]
	v_mfma_f32_16x16x32_bf16 v[18:21], v[142:145], v[188:191], v[18:21]
	s_setprio 0
	s_barrier
	s_add_u32 s50, s50, 0x80080
	s_addc_u32 s51, s51, 0
	s_add_i32 s52, s52, s56
	s_mov_b32 m0, s52
	s_nop 0
	global_load_lds_dwordx4 v162, s[50:51]
	s_add_i32 m0, s52, 0x2000
	s_nop 0
	global_load_lds_dwordx4 v164, s[50:51]
	s_waitcnt vmcnt(10)
	s_barrier
	s_setprio 1
	v_mfma_f32_16x16x32_bf16 v[46:49], v[192:195], v[146:149], v[46:49]
	v_mfma_f32_16x16x32_bf16 v[38:41], v[200:203], v[146:149], v[38:41]
	v_mfma_f32_16x16x32_bf16 v[30:33], v[192:195], v[154:157], v[30:33]
	v_mfma_f32_16x16x32_bf16 v[22:25], v[200:203], v[154:157], v[22:25]
	v_mfma_f32_16x16x32_bf16 v[14:17], v[192:195], v[176:179], v[14:17]
	v_mfma_f32_16x16x32_bf16 v[10:13], v[200:203], v[176:179], v[10:13]
	v_mfma_f32_16x16x32_bf16 v[6:9], v[192:195], v[184:187], v[6:9]
	v_mfma_f32_16x16x32_bf16 v[2:5], v[200:203], v[184:187], v[2:5]
	v_mfma_f32_16x16x32_bf16 v[46:49], v[196:199], v[150:153], v[46:49]
	v_mfma_f32_16x16x32_bf16 v[38:41], v[204:207], v[150:153], v[38:41]
	v_mfma_f32_16x16x32_bf16 v[30:33], v[196:199], v[158:161], v[30:33]
	v_mfma_f32_16x16x32_bf16 v[22:25], v[204:207], v[158:161], v[22:25]
	v_mfma_f32_16x16x32_bf16 v[14:17], v[196:199], v[180:183], v[14:17]
	v_mfma_f32_16x16x32_bf16 v[10:13], v[204:207], v[180:183], v[10:13]
	v_mfma_f32_16x16x32_bf16 v[6:9], v[196:199], v[188:191], v[6:9]
	v_mfma_f32_16x16x32_bf16 v[2:5], v[204:207], v[188:191], v[2:5]
	s_setprio 0
	s_add_i32 s80, s80, 2
	s_add_u32 s48, s48, 0x100
	s_addc_u32 s49, s49, 0
	s_add_u32 s74, s74, 0x100
	s_addc_u32 s75, s75, 0
	s_cmp_gt_u32 s80, s87
	s_barrier
	s_cbranch_scc0 .LBB0_1098
